# w_in phase split changed: part 1 = 64 bf16 units beside 3 fp8 units on each of 192 workgroups; part 2 = last 192 fp8 units on 64 workgroups beside pooling and GLA pre-pass on 192 workgroups
# baseline (speedup 1.0000x reference)
; __global__ void __launch_bounds__(NWAVES * 64, 2) mega_fwd(Args A) {
;     ...
;     for (int step = 0; step < 3 * DEPTH; ++step) {
;         const int l = step / 3, kind = step - 3 * l;
;         unsigned char* wl = ws + WS_W + (size_t)l * LW_END;
;         const unsigned long long* ssq = (const unsigned long long*)(ws + WS_CTL + CTL_SSQ) + (size_t)step * NTOK; unsigned long long* ssq_next = (unsigned long long*)(ws + WS_CTL + CTL_SSQ) + (size_t)(step + 1) * NTOK;
;         if (kind != 1) {
;             { pg8::Gemm g{H, (const bf16*)(wl + (kind == 0 ? LW_WI1 : LW_WI2)), NTOK, NWI, DM}; pg8::StaticOrder S; S.init(NTOK, NWI, G, bx);
;               pg8::EpiSwiglu E{ACT, DFF, ssq};
;               pg8::gemm_phase<pg8::EpiSwiglu, pg8::StaticOrder, true, true>(lds + RING_OFF, g, S, E); }
;             { const int rem1 = ((NTOK / 256) * (NWI / 256)) % G;
;               conv_until(A, lds, l * TL_LAYER + (kind == 0 ? TL_WIN : TL_LAYER), (rem1 != 0 && bx >= rem1) ? 3 : 0); }
;             xcd_barrier(bar);
;         } else {
;             const bool std256 = (G == 256);
;             unsigned char* XB8 = ws + WS_X;
; #pragma unroll 1
;             for (int part = 0; part < 3; ++part) {
;                 bool do16, do8; int i16, n16, g8, c8, i8, n8;
;                 if (std256) { do16 = part == 0 || (part == 1 && bx < 64); i16 = part ? 2 : 0; n16 = part ? 1 : 2;
;                               do8 = (part == 1 && bx >= 64) || (part == 2 && bx < 128); g8 = part == 1 ? 192 : 128; c8 = part == 1 ? bx - 64 : bx; i8 = part == 1 ? 0 : 3; n8 = part == 1 ? 2 : 3; }
;                 else { do16 = part == 0; i16 = 0; n16 = 1 << 20; do8 = part == 1; g8 = G; c8 = bx; i8 = 0; n8 = 1 << 20; }
;                 if (do16) { pg8::Gemm g{H, (const bf16*)(wl + LW_WIN), NTOK, C_GATE, DM}; pg8::RangeOrder S; S.init(NTOK, C_GATE, G, bx); S.i0 = i16; S.n = n16;
;                     pg8::EpiProj E{PROJ, NPROJ, (const float*)A.in[7] + (size_t)l * 6144, 1 << 20, ssq, 1.0f};
;                     pg8::gemm_phase<pg8::EpiProj, pg8::RangeOrder, true, true>(lds + RING_OFF, g, S, E); }
;                 if (do8) { pg8::Gemm g{(const bf16*)XB8, (const bf16*)(wl + LW_WIN + WIN8_OFF), NTOK, 6144, DM / 2}; pg8::RangeOrder S; S.init(NTOK, 6144, g8, c8); S.i0 = i8; S.n = n8;
.LBB0_284:
	v_writelane_b32 v252, s64, 42
	s_nop 1
	v_writelane_b32 v252, s65, 43
	v_writelane_b32 v252, s66, 44
	v_writelane_b32 v252, s67, 45
	v_writelane_b32 v252, s68, 46
	v_writelane_b32 v252, s69, 47
	v_writelane_b32 v252, s70, 48
	v_writelane_b32 v252, s71, 49
	v_writelane_b32 v252, s72, 50
	v_writelane_b32 v252, s73, 51
	v_writelane_b32 v252, s74, 52
	v_writelane_b32 v252, s75, 53
	v_writelane_b32 v252, s76, 54
	v_writelane_b32 v252, s77, 55
	v_writelane_b32 v252, s78, 56
	v_writelane_b32 v252, s79, 57
	s_or_b64 exec, exec, s[0:1]
	s_cmpk_lg_i32 s95, 0x100
	s_cselect_b64 s[0:1], -1, 0
	s_and_b64 s[0:1], s[0:1], exec
	s_cselect_b32 s69, s95, 0xc0
	s_add_i32 s4, s97, 0xffffffc0
	s_cmpk_lg_i32 s95, 0x100
	s_cselect_b64 s[0:1], -1, 0
	s_and_b64 s[2:3], s[0:1], exec
	s_cselect_b32 s20, s97, s4
	v_readlane_b32 s4, v252, 2
	v_readlane_b32 s18, v252, 16
	v_readlane_b32 s19, v252, 17
	s_add_u32 s74, s18, 0x10000
	s_addc_u32 s2, s19, 0
	v_readlane_b32 s5, v252, 3
	v_readlane_b32 s6, v252, 4
	v_readlane_b32 s7, v252, 5
	v_readlane_b32 s8, v252, 6
	v_readlane_b32 s9, v252, 7
	v_readlane_b32 s10, v252, 8
	v_readlane_b32 s11, v252, 9
	v_readlane_b32 s12, v252, 10
	v_readlane_b32 s13, v252, 11
	v_readlane_b32 s14, v252, 12
	v_readlane_b32 s15, v252, 13
	v_readlane_b32 s16, v252, 14
	v_readlane_b32 s17, v252, 15
	v_writelane_b32 v252, s2, 58
	s_add_u32 s2, s18, 0x35e00000
	s_addc_u32 s3, s19, 0
	s_add_u32 s88, s18, 0x3b600000
	s_addc_u32 s89, s19, 0
	v_writelane_b32 v252, s2, 59
	s_add_u32 s12, s18, 0x45e00000
	s_addc_u32 s13, s19, 0
	v_writelane_b32 v252, s3, 60
	v_writelane_b32 v252, s12, 61
	s_add_u32 s2, s18, 0x4c200000
	v_writelane_b32 v252, s13, 62
	s_addc_u32 s3, s19, 0
	v_writelane_b32 v252, s2, 63
	s_waitcnt vmcnt(15)
	v_mov_b32_e32 v3, 0
	v_mov_b32_e32 v216, 1
	v_writelane_b32 v253, s3, 0
	s_add_u32 s2, s18, 0x4e200000
	s_addc_u32 s3, s19, 0
	v_writelane_b32 v253, s2, 1
	v_mov_b32_e32 v217, 0x7f7f7f7f
	v_mov_b32_e32 v225, 0x43e00000
	v_writelane_b32 v253, s3, 2
	s_add_u32 s2, s18, 0x4fa00000
	s_addc_u32 s3, s19, 0
	v_writelane_b32 v253, s2, 3
	v_mov_b64_e32 v[226:227], 0x2ff
	v_mov_b32_e32 v222, 0x41b17218
	v_writelane_b32 v253, s3, 4
	s_add_u32 s2, s18, 0x4fb00000
	s_addc_u32 s3, s19, 0
	v_writelane_b32 v253, s2, 5
	v_mbcnt_hi_u32_b32 v223, -1, v76
	v_mov_b32_e32 v224, 0xf149f2ca
	v_writelane_b32 v253, s3, 6
	s_add_u32 s2, s18, 0x200000
	v_writelane_b32 v253, s2, 7
	s_addc_u32 s2, s19, 0
	s_cmpk_lt_i32 s97, 0x580
	v_writelane_b32 v253, s2, 8
	s_cselect_b64 s[2:3], -1, 0
	v_writelane_b32 v253, s2, 9
	s_ashr_i32 s21, s97, 31
	s_movk_i32 s75, 0xc0
	v_writelane_b32 v253, s3, 10
	s_lshr_b32 s2, s21, 29
	s_add_i32 s3, s97, s2
	s_ashr_i32 s2, s3, 3
	s_and_b32 s3, s3, -8
	s_sub_i32 s5, s97, s3
	s_ashr_i32 s3, s95, 31
	s_add_u32 s6, s18, 0x4200
	v_writelane_b32 v253, s3, 11
	s_addc_u32 s7, s19, 0
	v_writelane_b32 v253, s6, 12
	s_movk_i32 s76, 0x300
	s_movk_i32 s77, 0x5400
	v_writelane_b32 v253, s7, 13
	s_add_u32 s6, s18, 0x4400
	s_addc_u32 s7, s19, 0
	v_writelane_b32 v253, s6, 14
	s_movk_i32 s81, 0x7fff
	s_mov_b32 s82, 0xffff0000
	v_writelane_b32 v253, s7, 15
	s_add_u32 s6, s18, 0x4500
	s_addc_u32 s7, s19, 0
	v_writelane_b32 v253, s6, 16
	s_movk_i32 s61, 0x1110
	s_movk_i32 s84, 0x15ff
	v_writelane_b32 v253, s7, 17
	s_add_u32 s6, s18, 0x4600
	s_addc_u32 s7, s19, 0
	v_writelane_b32 v253, s6, 18
	s_mov_b32 s85, 0xc3e00000
	s_movk_i32 s33, 0xff
	v_writelane_b32 v253, s7, 19
	s_add_u32 s6, s18, 0x4700
	s_addc_u32 s7, s19, 0
	v_writelane_b32 v253, s6, 20
	s_movk_i32 s66, 0x90
	s_mov_b32 s96, 0x2aaaaaab
	v_writelane_b32 v253, s7, 21
	s_add_u32 s6, s18, 0x4800
	s_addc_u32 s7, s19, 0
	v_writelane_b32 v253, s6, 22
	s_movk_i32 s36, 0x190
	s_movk_i32 s37, 0xff40
	v_writelane_b32 v253, s7, 23
	s_add_u32 s6, s18, 0x4900
	s_addc_u32 s7, s19, 0
	v_writelane_b32 v253, s6, 24
	s_movk_i32 s38, 0x567
	s_movk_i32 s39, 0x1500
	v_writelane_b32 v253, s7, 25
	s_add_u32 s6, s18, 0x4a00
	s_addc_u32 s7, s19, 0
	v_writelane_b32 v253, s6, 26
	s_movk_i32 s56, 0x1800
	s_movk_i32 s57, 0xc80
	v_writelane_b32 v253, s7, 27
	s_add_u32 s6, s18, 0x4b00
	s_addc_u32 s7, s19, 0
	v_writelane_b32 v253, s6, 28
	s_movk_i32 s58, 0x3ff
	s_mov_b32 s80, 0xefa18f08
	v_writelane_b32 v253, s7, 29
	s_add_u32 s6, s18, 0x4c00
	s_addc_u32 s7, s19, 0
	v_writelane_b32 v253, s6, 30
	s_mov_b32 s62, 0
	s_mov_b32 s94, 0x3e000000
	v_writelane_b32 v253, s7, 31
	s_add_u32 s6, s18, 0x4d00
	s_addc_u32 s7, s19, 0
	v_writelane_b32 v253, s6, 32
	s_waitcnt lgkmcnt(0)
	s_barrier
; __global__ void __launch_bounds__(NWAVES * 64, 2) mega_fwd(Args A) {
;     ...
;             { const int rem1 = ((NTOK / 256) * (NWI / 256)) % G;
;               conv_until(A, lds, l * TL_LAYER + (kind == 0 ? TL_WIN : TL_LAYER), (rem1 != 0 && bx >= rem1) ? 3 : 0); }
;             xcd_barrier(bar);
;         } else {
;             const bool std256 = (G == 256);
;             unsigned char* XB8 = ws + WS_X;
; #pragma unroll 1
;             for (int part = 0; part < 3; ++part) {
;                 bool do16, do8; int i16, n16, g8, c8, i8, n8;
;                 if (std256) { do16 = part == 0 || (part == 1 && bx < 64); i16 = part ? 2 : 0; n16 = part ? 1 : 2;
;                               do8 = (part == 1 && bx >= 64) || (part == 2 && bx < 128); g8 = part == 1 ? 192 : 128; c8 = part == 1 ? bx - 64 : bx; i8 = part == 1 ? 0 : 3; n8 = part == 1 ? 2 : 3; }
;                 else { do16 = part == 0; i16 = 0; n16 = 1 << 20; do8 = part == 1; g8 = G; c8 = bx; i8 = 0; n8 = 1 << 20; }
;                 if (do16) { pg8::Gemm g{H, (const bf16*)(wl + LW_WIN), NTOK, C_GATE, DM}; pg8::RangeOrder S; S.init(NTOK, C_GATE, G, bx); S.i0 = i16; S.n = n16;
;                     pg8::EpiProj E{PROJ, NPROJ, (const float*)A.in[7] + (size_t)l * 6144, 1 << 20, ssq, 1.0f};
;                     pg8::gemm_phase<pg8::EpiProj, pg8::RangeOrder, true, true>(lds + RING_OFF, g, S, E); }
;                 if (do8) { pg8::Gemm g{(const bf16*)XB8, (const bf16*)(wl + LW_WIN + WIN8_OFF), NTOK, 6144, DM / 2}; pg8::RangeOrder S; S.init(NTOK, 6144, g8, c8); S.i0 = i8; S.n = n8;
;                     pg8::EpiGate8 E{(unsigned char*)(PROJ + C_GATE), NPROJ * 2, (const float*)A.in[7] + (size_t)l * 6144, ssq, 1.0f / 2048.0f};
;                     pg8::gemm_phase<pg8::EpiGate8, pg8::RangeOrder, true, true, true>(lds + RING_OFF, g, S, E); }
;                 if (part == 1) xcd_barrier(bar);
;                 if (part == 2 && (!std256 || bx >= 128)) { const int mb = std256 ? bx - 128 : bx, ms = std256 ? 128 : G;
;                     if ((ms & 3) == 0) pool_units(lds, PROJ, (const bf16*)(ws + WS_WPT) + (size_t)l * 4 * 192 * 192, Y + (size_t)NTOK * BRW, mb, ms, 512);
;                     else for (int u = mb; u < 512; u += ms) pool_units(lds, PROJ, (const bf16*)(ws + WS_WPT) + (size_t)l * 4 * 192 * 192, Y + (size_t)NTOK * BRW, u, 512, 512);
	v_writelane_b32 v253, s7, 33
	s_add_u32 s6, s18, 0x4e00
	s_addc_u32 s7, s19, 0
	v_writelane_b32 v253, s6, 34
	s_nop 1
	v_writelane_b32 v253, s7, 35
	s_add_u32 s6, s18, 0x4f00
	s_addc_u32 s7, s19, 0
	v_writelane_b32 v253, s6, 36
	s_nop 1
	v_writelane_b32 v253, s7, 37
	s_add_u32 s6, s18, 0x5000
	s_addc_u32 s7, s19, 0
	v_writelane_b32 v253, s6, 38
	s_nop 1
	v_writelane_b32 v253, s7, 39
	s_add_u32 s6, s18, 0x5100
	s_addc_u32 s7, s19, 0
	v_writelane_b32 v253, s6, 40
	s_nop 1
	v_writelane_b32 v253, s7, 41
	s_add_u32 s6, s18, 0x5200
	s_addc_u32 s7, s19, 0
	v_writelane_b32 v253, s6, 42
	s_nop 1
	v_writelane_b32 v253, s7, 43
	s_add_u32 s6, s18, 0x5300
	s_addc_u32 s7, s19, 0
	v_writelane_b32 v253, s6, 44
	s_nop 1
	v_writelane_b32 v253, s7, 45
	s_add_u32 s6, s18, 0x7400
	s_addc_u32 s7, s19, 0
	v_writelane_b32 v253, s6, 46
	s_nop 1
	v_writelane_b32 v253, s7, 47
	s_add_u32 s6, s18, 0x7500
	s_addc_u32 s7, s19, 0
	v_writelane_b32 v253, s6, 48
	s_cmpk_eq_i32 s95, 0x100
	s_nop 0
	v_writelane_b32 v253, s7, 49
	s_cselect_b64 s[6:7], -1, 0
	s_add_u32 s72, s18, 0x2fe00000
	s_addc_u32 s73, s19, 0
	v_writelane_b32 v253, s6, 50
	s_cmp_lt_i32 s97, 64
	s_nop 0
	v_writelane_b32 v253, s7, 51
	s_cselect_b64 s[6:7], -1, 0
	v_writelane_b32 v253, s6, 52
	s_cmp_gt_i32 s97, 63
	s_nop 0
	v_writelane_b32 v253, s7, 53
	s_cselect_b64 s[6:7], -1, 0
	v_writelane_b32 v253, s6, 54
	s_cmpk_lt_i32 s97, 0x80
	s_nop 0
	v_writelane_b32 v253, s7, 55
	s_cselect_b64 s[6:7], -1, 0
	v_writelane_b32 v253, s6, 56
	s_sub_i32 s3, s97, 64
	s_nop 0
	v_writelane_b32 v253, s7, 57
	s_add_u32 s6, s18, 0x3b602400
	v_writelane_b32 v253, s3, 58
	s_addc_u32 s7, s19, 0
	v_writelane_b32 v253, s6, 59
	s_cmpk_gt_i32 s97, 0x3f
	s_nop 0
	v_writelane_b32 v253, s7, 60
	s_cselect_b64 s[6:7], -1, 0
	s_or_b64 s[0:1], s[6:7], s[0:1]
	v_writelane_b32 v253, s0, 61
	s_nop 1
	v_writelane_b32 v253, s1, 62
	s_and_b32 s0, s69, 3
	s_cmp_lg_u32 s0, 0
	s_cselect_b64 s[0:1], -1, 0
	v_writelane_b32 v253, s0, 63
	s_cmpk_lt_i32 s20, 0x200
	s_nop 0
	v_writelane_b32 v254, s1, 0
	s_cselect_b64 s[0:1], -1, 0
	v_writelane_b32 v254, s0, 1
	s_nop 1
	v_writelane_b32 v254, s1, 2
	s_add_u32 s0, s18, 0x46a00000
	s_addc_u32 s1, s19, 0
	v_writelane_b32 v254, s0, 3
	s_and_b32 s4, s20, 3
	s_nop 0
	v_writelane_b32 v254, s1, 4
	s_mul_i32 s0, s4, 0x12000
	s_add_u32 s0, s34, s0
	v_writelane_b32 v254, s0, 5
	v_writelane_b32 v254, s34, 6
	s_addc_u32 s0, s35, 0
	s_lshl_b32 s68, 2, s4
	v_writelane_b32 v254, s35, 7
	v_writelane_b32 v254, s0, 8
	s_lshl_b32 s1, s20, 4
	s_lshl_b32 s0, s69, 4
	s_add_u32 s22, s18, 0x4fc00000
	v_writelane_b32 v254, s0, 9
	s_addc_u32 s23, s19, 0
	s_lshl_b32 s0, s20, 6
	s_and_b32 s0, s0, 0x7c0
	v_writelane_b32 v254, s1, 10
	s_and_b32 s1, s1, 0xfffff800
	s_or_b32 s0, s1, s0
	s_ashr_i32 s1, s0, 31
	v_writelane_b32 v254, s0, 11
	s_bfe_u32 s3, s20, 0x20005
	s_mov_b32 s35, 0
	v_writelane_b32 v254, s1, 12
	s_mul_i32 s0, s3, 0x60
	v_writelane_b32 v254, s20, 13
	s_add_i32 s1, s0, 0x920
	v_writelane_b32 v254, s1, 14
	v_writelane_b32 v254, s0, 15
	s_bitset1_b32 s0, 11
	s_cmpk_lt_i32 s95, 0x61
	v_writelane_b32 v254, s0, 16
	s_cselect_b64 s[0:1], -1, 0
	s_cmpk_gt_i32 s95, 0x60
	v_writelane_b32 v254, s0, 17
	s_cselect_b64 s[6:7], -1, 0
	s_cmp_lt_i32 s97, 48
	v_writelane_b32 v254, s1, 18
	s_cselect_b64 s[0:1], -1, 0
	v_writelane_b32 v254, s0, 19
	s_cmpk_lt_i32 s97, 0x100
	s_nop 0
	v_writelane_b32 v254, s1, 20
	s_cselect_b64 s[0:1], -1, 0
	v_writelane_b32 v254, s0, 21
	s_nop 1
	v_writelane_b32 v254, s1, 22
	s_sub_i32 s0, s97, 48
	v_writelane_b32 v254, s0, 23
	s_cmpk_lt_i32 s97, 0x130
	s_mul_hi_i32 s0, s97, 0x55555556
	s_cselect_b64 s[8:9], -1, 0
	s_lshr_b32 s1, s0, 31
	s_add_i32 s10, s0, s1
	s_mul_i32 s0, s10, -3
	s_add_i32 s0, s0, s97
	v_writelane_b32 v254, s8, 24
	s_lshl_b32 s1, s0, 13
	s_add_i32 s1, s1, 0x8000
	v_writelane_b32 v254, s9, 25
	v_writelane_b32 v254, s1, 26
	s_sub_i32 s1, s95, 48
	v_writelane_b32 v254, s1, 27
	s_lshl_b32 s8, s10, 5
	s_mul_i32 s1, s10, 0x1c4000
	v_writelane_b32 v254, s8, 28
	s_mul_hi_i32 s8, s8, 0xe200
	s_add_u32 s14, s22, s1
	s_addc_u32 s15, s23, s8
	s_add_u32 s8, s14, 0xe000
	v_writelane_b32 v254, s14, 29
	s_addc_u32 s9, s15, 0
	s_lshl_b32 s1, s10, 9
	s_lshl_b32 s0, s0, 6
	v_writelane_b32 v254, s15, 30
	s_and_b32 s11, s1, 0xfffff800
	s_ashr_i32 s1, s0, 31
	v_writelane_b32 v254, s8, 31
	s_cmp_gt_i32 s97, 47
	s_nop 0
	v_writelane_b32 v254, s9, 32
	s_cselect_b64 s[8:9], -1, 0
	v_writelane_b32 v254, s8, 33
	s_mov_b64 s[14:15], s[6:7]
	s_add_i32 s6, s97, s95
	s_addk_i32 s6, 0xffa0
	v_writelane_b32 v254, s9, 34
	s_cmpk_lt_i32 s6, 0x100
	s_cselect_b32 s8, 2, 4
	v_writelane_b32 v254, s14, 35
	s_and_b64 s[6:7], s[14:15], exec
	s_cselect_b32 s6, s8, 0
	v_writelane_b32 v254, s15, 36
	v_writelane_b32 v254, s6, 37
	s_add_u32 s6, s18, 0x47600000
	v_writelane_b32 v254, s6, 38
	s_addc_u32 s6, s19, 0
	v_writelane_b32 v254, s6, 39
	s_lshl_b32 s14, s95, 5
	s_lshl_b32 s6, s5, 5
	s_cmp_lt_i32 s5, 0
	s_movk_i32 s7, 0xb1
; __global__ void __launch_bounds__(NWAVES * 64, 2) mega_fwd(Args A) {
;     ...
;             { const int rem1 = ((NTOK / 256) * (NWI / 256)) % G;
;               conv_until(A, lds, l * TL_LAYER + (kind == 0 ? TL_WIN : TL_LAYER), (rem1 != 0 && bx >= rem1) ? 3 : 0); }
;             xcd_barrier(bar);
;         } else {
;             const bool std256 = (G == 256);
;             unsigned char* XB8 = ws + WS_X;
; #pragma unroll 1
;             for (int part = 0; part < 3; ++part) {
;                 bool do16, do8; int i16, n16, g8, c8, i8, n8;
;                 if (std256) { do16 = part == 0 || (part == 1 && bx < 64); i16 = part ? 2 : 0; n16 = part ? 1 : 2;
;                               do8 = (part == 1 && bx >= 64) || (part == 2 && bx < 128); g8 = part == 1 ? 192 : 128; c8 = part == 1 ? bx - 64 : bx; i8 = part == 1 ? 0 : 3; n8 = part == 1 ? 2 : 3; }
;                 else { do16 = part == 0; i16 = 0; n16 = 1 << 20; do8 = part == 1; g8 = G; c8 = bx; i8 = 0; n8 = 1 << 20; }
;                 if (do16) { pg8::Gemm g{H, (const bf16*)(wl + LW_WIN), NTOK, C_GATE, DM}; pg8::RangeOrder S; S.init(NTOK, C_GATE, G, bx); S.i0 = i16; S.n = n16;
;                     pg8::EpiProj E{PROJ, NPROJ, (const float*)A.in[7] + (size_t)l * 6144, 1 << 20, ssq, 1.0f};
;                     pg8::gemm_phase<pg8::EpiProj, pg8::RangeOrder, true, true>(lds + RING_OFF, g, S, E); }
;                 if (do8) { pg8::Gemm g{(const bf16*)XB8, (const bf16*)(wl + LW_WIN + WIN8_OFF), NTOK, 6144, DM / 2}; pg8::RangeOrder S; S.init(NTOK, 6144, g8, c8); S.i0 = i8; S.n = n8;
;                     pg8::EpiGate8 E{(unsigned char*)(PROJ + C_GATE), NPROJ * 2, (const float*)A.in[7] + (size_t)l * 6144, ssq, 1.0f / 2048.0f};
;                     pg8::gemm_phase<pg8::EpiGate8, pg8::RangeOrder, true, true, true>(lds + RING_OFF, g, S, E); }
;                 if (part == 1) xcd_barrier(bar);
;                 if (part == 2 && (!std256 || bx >= 128)) { const int mb = std256 ? bx - 128 : bx, ms = std256 ? 128 : G;
;                     if ((ms & 3) == 0) pool_units(lds, PROJ, (const bf16*)(ws + WS_WPT) + (size_t)l * 4 * 192 * 192, Y + (size_t)NTOK * BRW, mb, ms, 512);
;                     else for (int u = mb; u < 512; u += ms) pool_units(lds, PROJ, (const bf16*)(ws + WS_WPT) + (size_t)l * 4 * 192 * 192, Y + (size_t)NTOK * BRW, u, 512, 512);
	s_cselect_b32 s7, s7, 0xb0
	s_mul_i32 s7, s5, s7
	s_mul_i32 s5, s5, 33
	s_cselect_b32 s5, s5, s6
	s_add_i32 s7, s7, s2
	s_mul_hi_i32 s6, s7, 0x2e8ba2e9
	s_lshr_b32 s8, s6, 31
	s_ashr_i32 s6, s6, 6
	s_add_i32 s6, s6, s8
	s_mul_i32 s8, s6, 0x160
	s_sub_i32 s7, s7, s8
	s_bfe_u32 s8, s7, 0x3001c
	s_add_i32 s8, s7, s8
	s_and_b32 s9, s8, 0xfff8
	s_sub_i32 s7, s7, s9
	s_lshl_b32 s6, s6, 3
	s_sext_i32_i16 s8, s8
	s_sext_i32_i16 s7, s7
	s_add_i32 s16, s6, s7
	s_ashr_i32 s6, s8, 3
	v_writelane_b32 v254, s6, 40
	s_lshr_b32 s6, s8, 3
	s_bfe_i64 s[6:7], s[6:7], 0x100000
	s_lshl_b64 s[6:7], s[6:7], 20
	v_writelane_b32 v254, s6, 41
	s_ashr_i32 s17, s16, 31
	s_nop 0
	v_writelane_b32 v254, s7, 42
	s_mov_b32 s6, s16
	v_writelane_b32 v254, s6, 43
	s_nop 1
	v_writelane_b32 v254, s7, 44
	s_lshl_b64 s[6:7], s[16:17], 20
	s_add_u32 s6, s90, s6
	s_addc_u32 s7, s91, s7
	s_add_u32 s8, s6, 0x80000
	s_addc_u32 s9, s7, 0
	v_writelane_b32 v254, s8, 45
	s_nop 1
	v_writelane_b32 v254, s9, 46
	s_add_u32 s8, s6, 0x2000
	v_writelane_b32 v254, s6, 47
	s_addc_u32 s9, s7, 0
	s_add_i32 s2, s5, s2
	s_ashr_i32 s5, s2, 31
	s_lshr_b32 s5, s5, 26
	s_add_i32 s5, s2, s5
	v_writelane_b32 v254, s7, 48
	s_and_b32 s6, s5, 0xffc0
	s_sub_i32 s2, s2, s6
	s_bfe_i32 s6, s2, 0x80000
	s_bfe_u32 s6, s6, 0x3000c
	s_add_i32 s6, s2, s6
	s_and_b32 s7, s6, 0xf8
	s_sub_i32 s2, s2, s7
	s_ashr_i32 s5, s5, 6
	s_lshl_b32 s5, s5, 3
	s_sext_i32_i8 s2, s2
	s_add_i32 s5, s5, s2
	s_bfe_i32 s2, s6, 0x80000
	v_writelane_b32 v254, s8, 49
	s_sext_i32_i16 s2, s2
	s_ashr_i32 s6, s2, 3
	v_writelane_b32 v254, s9, 50
	s_lshr_b32 s2, s2, 3
	v_writelane_b32 v254, s6, 51
	s_bfe_i64 s[6:7], s[2:3], 0x100000
	v_writelane_b32 v254, s6, 52
	s_mul_hi_i32 s2, s5, 0x60000
	s_nop 0
	v_writelane_b32 v254, s7, 53
	v_writelane_b32 v254, s5, 54
	s_mul_i32 s5, s5, 0x60000
	s_add_u32 s6, s12, s5
	s_addc_u32 s7, s13, s2
	s_add_u32 s8, s6, 0x30000
	s_addc_u32 s9, s7, 0
	v_writelane_b32 v254, s8, 55
	s_nop 1
	v_writelane_b32 v254, s9, 56
	s_add_u32 s8, s6, 0x2000
	v_writelane_b32 v254, s6, 57
	s_addc_u32 s9, s7, 0
	s_abs_i32 s2, s95
	v_cvt_f32_u32_e32 v1, s2
	v_writelane_b32 v254, s7, 58
	s_sub_i32 s5, 0, s2
	v_writelane_b32 v254, s8, 59
	v_rcp_iflag_f32_e32 v1, v1
	s_nop 0
	v_writelane_b32 v254, s9, 60
	v_mul_f32_e32 v1, 0x4f7ffffe, v1
	v_cvt_u32_f32_e32 v1, v1
	s_nop 0
	v_readfirstlane_b32 s6, v1
	s_mul_i32 s5, s5, s6
	s_mul_hi_u32 s5, s6, s5
	s_add_i32 s6, s6, s5
	s_mul_hi_u32 s5, s6, 0x580
	s_mul_i32 s5, s5, s2
	s_sub_i32 s5, 0x580, s5
	s_sub_i32 s6, s5, s2
	s_cmp_ge_u32 s5, s2
	s_cselect_b32 s5, s6, s5
	s_sub_i32 s6, s5, s2
	s_cmp_ge_u32 s5, s2
	s_cselect_b32 s2, s6, s5
	s_cmp_lg_u32 s2, 0
	s_cselect_b64 s[6:7], -1, 0
	s_cmp_ge_i32 s97, s2
	s_cselect_b64 s[8:9], -1, 0
	s_and_b64 s[6:7], s[6:7], s[8:9]
	s_mul_i32 s2, s4, 0xc0
	v_writelane_b32 v254, s6, 61
	s_and_b64 s[4:5], s[6:7], exec
	s_cselect_b32 s4, 3, 0
	v_writelane_b32 v254, s7, 62
	v_writelane_b32 v255, s2, 0
	s_lshl_b32 s2, s2, 1
	v_writelane_b32 v254, s4, 63
	s_add_u32 s4, s88, s2
	s_addc_u32 s5, s89, 0
	v_writelane_b32 v255, s4, 1
	s_and_b32 s2, s10, 3
	s_mulk_i32 s2, 0x300
	v_writelane_b32 v255, s5, 2
	s_mul_i32 s4, s11, 0xc00
	s_lshl_b32 s5, s97, 6
	s_or_b32 s2, s4, s2
	s_lshl_b64 s[0:1], s[0:1], 2
	v_writelane_b32 v255, s5, 3
	s_lshl_b32 s5, s95, 6
	s_mul_hi_i32 s4, s11, 0xc00
	s_add_u32 s0, s2, s0
	s_addc_u32 s1, s4, s1
	s_add_u32 s0, s18, s0
	v_writelane_b32 v255, s5, 4
	s_addc_u32 s1, s19, s1
	v_writelane_b32 v255, s0, 5
	s_mul_i32 s2, s95, 0x18000
	s_add_i32 s93, 0, 0x20180
	v_writelane_b32 v255, s1, 6
	s_mul_i32 s0, s3, 0xc0
	s_mul_hi_i32 s3, s14, 0xc00
	v_writelane_b32 v255, s2, 7
	s_lshl_b32 s1, s97, 9
	s_lshl_b32 s0, s0, 1
	v_writelane_b32 v255, s3, 8
	s_mul_i32 s2, s95, 0xa8000
	v_writelane_b32 v255, s14, 9
	s_mul_hi_i32 s3, s14, 0x5400
	v_writelane_b32 v255, s2, 10
	s_add_i32 s60, 0, 0x20184
	v_mov_b32_e32 v1, 0x358637bd
	v_writelane_b32 v255, s3, 11
	v_writelane_b32 v255, s1, 12
	s_lshl_b32 s1, s95, 11
	v_writelane_b32 v255, s1, 13
	s_lshl_b32 s1, s95, 4
	v_writelane_b32 v255, s1, 14
	s_lshl_b32 s1, s95, 10
	v_writelane_b32 v255, s1, 15
	s_lshl_b32 s1, s95, 9
	v_writelane_b32 v255, s1, 16
	s_add_i32 s1, 0, 0x20160
	v_writelane_b32 v255, s1, 17
	s_add_i32 s1, 0, 0x20164
	v_writelane_b32 v255, s1, 18
	s_add_i32 s1, 0, 0x2d00
	v_writelane_b32 v255, s1, 19
	v_writelane_b32 v255, s0, 20
	s_add_i32 s64, 0, 0x12600
	s_nop 0
	v_writelane_b32 v255, s1, 21
	s_add_i32 s0, 0, 0xf000
	v_writelane_b32 v255, s0, 22
	s_add_i32 s0, 0, 0x8800
	v_writelane_b32 v255, s0, 23
	v_writelane_b32 v255, s90, 24
	s_nop 1
	v_writelane_b32 v255, s91, 25
	v_writelane_b32 v255, s69, 26
	v_writelane_b32 v255, s88, 27
	s_nop 1
	v_writelane_b32 v255, s89, 28
	v_writelane_b32 v255, s21, 29
	v_writelane_b32 v255, s22, 30
	v_writelane_b32 v255, s23, 31
	v_writelane_b32 v255, s93, 32
	v_writelane_b32 v255, s60, 33
	v_writelane_b32 v255, s92, 34
	s_nop 1
	v_writelane_b32 v255, s93, 35
	s_branch .LBB0_287

; __global__ void __launch_bounds__(NWAVES * 64, 2) mega_fwd(Args A) {
;     ...
;                 if (std256) { do16 = part == 0 || (part == 1 && bx < 64); i16 = part ? 2 : 0; n16 = part ? 1 : 2;
;                               do8 = (part == 1 && bx >= 64) || (part == 2 && bx < 128); g8 = part == 1 ? 192 : 128; c8 = part == 1 ? bx - 64 : bx; i8 = part == 1 ? 0 : 3; n8 = part == 1 ? 2 : 3; }
;                 else { do16 = part == 0; i16 = 0; n16 = 1 << 20; do8 = part == 1; g8 = G; c8 = bx; i8 = 0; n8 = 1 << 20; }
;                 if (do16) { pg8::Gemm g{H, (const bf16*)(wl + LW_WIN), NTOK, C_GATE, DM}; pg8::RangeOrder S; S.init(NTOK, C_GATE, G, bx); S.i0 = i16; S.n = n16;
;                     pg8::EpiProj E{PROJ, NPROJ, (const float*)A.in[7] + (size_t)l * 6144, 1 << 20, ssq, 1.0f};
;                     pg8::gemm_phase<pg8::EpiProj, pg8::RangeOrder, true, true>(lds + RING_OFF, g, S, E); }
;                 if (do8) { pg8::Gemm g{(const bf16*)XB8, (const bf16*)(wl + LW_WIN + WIN8_OFF), NTOK, 6144, DM / 2}; pg8::RangeOrder S; S.init(NTOK, 6144, g8, c8); S.i0 = i8; S.n = n8;
;                     pg8::EpiGate8 E{(unsigned char*)(PROJ + C_GATE), NPROJ * 2, (const float*)A.in[7] + (size_t)l * 6144, ssq, 1.0f / 2048.0f};
;                     pg8::gemm_phase<pg8::EpiGate8, pg8::RangeOrder, true, true, true>(lds + RING_OFF, g, S, E); }
.LBB0_550:
	s_cmp_eq_u32 s63, 0
	v_readlane_b32 s4, v253, 50
	s_cselect_b64 s[2:3], -1, 0
	s_cmp_eq_u32 s63, 1
	v_readlane_b32 s5, v253, 51
	s_cselect_b64 s[0:1], -1, 0
	s_andn2_b64 vcc, exec, s[4:5]
	s_cbranch_vccnz .LBB0_552
	v_readlane_b32 s4, v253, 52
	v_readlane_b32 s5, v253, 53
	s_and_b64 s[4:5], s[4:5], s[0:1]
	s_or_b64 s[4:5], s[2:3], s[4:5]
	s_and_b64 s[2:3], s[2:3], exec
	v_readlane_b32 s2, v253, 54
	v_readlane_b32 s3, v253, 55
	s_cselect_b32 s40, 0, 2
	s_cselect_b32 s26, 2, 1
	s_and_b64 s[2:3], s[2:3], s[0:1]
	s_cmp_eq_u32 s63, 2
	v_readlane_b32 s8, v253, 52
	s_cselect_b64 s[6:7], -1, 0
	v_readlane_b32 s9, v253, 53
	s_and_b64 s[6:7], s[8:9], s[6:7]
	s_or_b64 s[2:3], s[2:3], s[6:7]
	s_and_b64 s[0:1], s[0:1], exec
	v_readlane_b32 s0, v253, 58
	s_cselect_b32 s42, s75, 64
	s_cselect_b32 s54, s0, s97
	s_cselect_b32 s25, 0, 9
	s_cselect_b32 s24, 3, 3
	s_mov_b64 s[0:1], s[2:3]
	s_mov_b64 s[2:3], s[4:5]
	s_andn2_b64 vcc, exec, s[2:3]
	s_cbranch_vccz .LBB0_553
	s_branch .LBB0_570
